# grid barrier: the arriving workgroup's L1 invalidate (buffer_inv sc1) issued at arrival instead of after the release (no cached loads while parked)
# speedup vs baseline: 1.0054x; 1.0054x over previous
; __device__ __forceinline__ void xcd_barrier(const XcdBarrier& b) {
;     asm volatile("s_waitcnt vmcnt(0)" ::: "memory");
;     __syncthreads();
;     if (threadIdx.x == 0) {
;         unsigned* bar = b.bar;
;         __builtin_amdgcn_s_waitcnt(0);
;         unsigned nloc = b.st[0], nx = b.st[1];
;         if (nloc == 0u) { xcd_barrier_complete(bar, b.x, nloc, nx); b.st[0] = nloc; b.st[1] = nx; }
; __global__ void __launch_bounds__(NTHR, 2) fwd_megakernel(Params P) {
;     ...
;         if (ph + 1 < ph_hi) { XcdBarrier b2; b2.bar = (unsigned*)ws + 4096; b2.x = MISC[16]; b2.st = MISC + 8; xcd_barrier(b2); }
.LBB0_438:
	s_add_i32 s76, s76, 1
	s_cmp_ge_i32 s76, s77
	s_mov_b64 s[0:1], -1
	s_cbranch_scc1 .LBB0_177
	v_readlane_b32 s0, v244, 24
	s_waitcnt vmcnt(0)
	s_nop 0
	v_mov_b32_e32 v1, s0
	ds_read_b32 v1, v1
	s_waitcnt vmcnt(0)
	s_waitcnt lgkmcnt(0)
	s_barrier
	v_readfirstlane_b32 s17, v1
	s_mov_b64 s[0:1], exec
	v_readlane_b32 s2, v245, 2
	v_readlane_b32 s3, v245, 3
	s_and_b64 s[2:3], s[0:1], s[2:3]
	s_mov_b64 exec, s[2:3]
	s_cbranch_execz .LBB0_176
	buffer_inv sc1
	v_readlane_b32 s2, v244, 25
	s_waitcnt vmcnt(0) expcnt(0) lgkmcnt(0)
	s_nop 0
	v_mov_b32_e32 v1, s2
	ds_read_b32 v3, v1
	v_readlane_b32 s2, v244, 26
	s_waitcnt lgkmcnt(0)
	v_cmp_ne_u32_e32 vcc, 0, v3
	v_mov_b32_e32 v1, s2
	ds_read_b32 v2, v1
	s_cbranch_vccnz .LBB0_455
	v_readlane_b32 s4, v245, 0
	v_readlane_b32 s5, v245, 1
	s_load_dwordx2 s[2:3], s[4:5], 0x4
	s_mov_b32 s19, 1
	s_waitcnt lgkmcnt(0)
	s_mul_i32 s18, s2, s33
	s_mul_i32 s18, s18, s3
	s_branch .LBB0_443

; __device__ __forceinline__ unsigned xb_ld(unsigned* p)              { return __hip_atomic_load(p, __ATOMIC_RELAXED, __HIP_MEMORY_SCOPE_AGENT); }
; #define XB_SPIN(cond, bar) do { unsigned _sp = 0; while (cond) { __builtin_amdgcn_s_sleep(1); \
;     if ((++_sp & 255u) == 0u) { if (xb_ld(&(bar)[XB_TMO])) break; if (_sp > XB_SPIN_CAP) { atomicAdd(&(bar)[XB_TMO], 1u); break; } } } } while (0)
; __device__ __forceinline__ void xcd_barrier(const XcdBarrier& b) {
;     ...
;             XB_SPIN(xb_ld(&bar[XB_XGEN(b.x)]) == gen, bar);
;             __builtin_amdgcn_fence(__ATOMIC_ACQUIRE, "agent");
;             asm volatile("s_waitcnt vmcnt(0)" ::: "memory");
.LBB0_470:
	s_or_b64 exec, exec, s[4:5]
	s_waitcnt vmcnt(0)
	s_waitcnt vmcnt(0)

; __device__ __forceinline__ unsigned xb_add(unsigned* p, unsigned v) { return __hip_atomic_fetch_add(p, v, __ATOMIC_RELAXED, __HIP_MEMORY_SCOPE_AGENT); }
; __device__ __forceinline__ void xcd_barrier(const XcdBarrier& b) {
;     ...
;             __builtin_amdgcn_fence(__ATOMIC_ACQUIRE, "agent");
;             xb_add(&bar[XB_XGEN(b.x)], 1u);
;             asm volatile("s_waitcnt vmcnt(0)" ::: "memory");
.LBB0_488:
	s_or_b64 exec, exec, s[2:3]
	s_mov_b64 s[2:3], exec
	v_mbcnt_lo_u32_b32 v1, s2, 0
	v_mbcnt_hi_u32_b32 v1, s3, v1
	v_cmp_eq_u32_e32 vcc, 0, v1
	s_waitcnt vmcnt(0)
	s_and_saveexec_b64 s[4:5], vcc
	s_cbranch_execz .LBB0_175
	s_add_i32 s88, s17, 0x900
	s_lshl_b64 s[8:9], s[88:89], 2
	v_readlane_b32 s17, v245, 29
	s_add_u32 s8, s17, s8
	v_readlane_b32 s17, v245, 30
	s_addc_u32 s9, s17, s9
	s_bcnt1_i32_b64 s2, s[2:3]
	v_mov_b32_e32 v1, s2
	global_atomic_add v0, v1, s[8:9]
	s_branch .LBB0_175
